# MLA attention loop: Q-fragment vmcnt ladder replaced by one wait before the loop, per-segment s_setprio flips removed (lgkmcnt ladders unchanged)
# speedup vs baseline: 1.0117x; 1.0117x over previous
; template <int DQK, bool SWA>
; DI void attn_item(const P& p, char* shm, int b, int head, int qtile) {
;     ...
;         {
;             constexpr int NG = DQK / 32;
;             const char* kl = Kb + l31 * KST + 16 * hh;
;             bf16x8 ka[3][4];
; #pragma unroll
;             for (int g0 = 0; g0 < 2; ++g0)
; #pragma unroll
;                 for (int i = 0; i < 4; ++i) ka[g0][i] = *(const bf16x8*)(kl + (i & 1) * 32 * KST + 32 * (2 * g0 + (i >> 1)));
;             __builtin_amdgcn_s_setprio(1);
; #pragma unroll
;             for (int g = 0; g < NG; ++g) {
;                 if (g + 2 < NG) {
; #pragma unroll
;                     for (int i = 0; i < 4; ++i) ka[(g + 2) % 3][i] = *(const bf16x8*)(kl + (i & 1) * 32 * KST + 32 * (2 * (g + 2) + (i >> 1)));
;                 }
;                 __builtin_amdgcn_sched_barrier(0);
; #pragma unroll
;                 for (int i = 0; i < 4; ++i) sT[i & 1] = MFMA32(ka[g % 3][i], qf[2 * g + (i >> 1)], sT[i & 1]);
;                 __builtin_amdgcn_sched_barrier(0);
;             }
;             __builtin_amdgcn_s_setprio(0);
;         }
;         const char* vl = Vb + l31 * VST + 8 * hh;
;         bf16x8 va[2][4];
;         auto vfrag = [&](int g, int v) {
;             const char* vp = vl + v * 32 * VST + 32 * g;
;             const s16x4 vlo = *(const s16x4*)vp, vhi = *(const s16x4*)(vp + 16);
;             return (bf16x8)__builtin_shufflevector(vlo, vhi, 0, 1, 2, 3, 4, 5, 6, 7);
;         };
; #pragma unroll
;         for (int v = 0; v < 4; ++v) va[0][v] = vfrag(0, v);
;         __builtin_amdgcn_sched_barrier(0);
;         const bool band = SWA && t >= 4;
;         const int kl0 = 64 * (lo + t - 4), qs = myp - CTXL;
;         float mx = -3.0e38f;
; #pragma unroll
;         for (int kb = 0; kb < 2; ++kb)
; #pragma unroll
;             for (int r = 0; r < 16; ++r) {
;                 if (band) { const int dd = qs - (kl0 + kb * 32 + crow(r, hh)); if (dd > 128 || dd < -128) sT[kb][r] = -3.0e37f; }
;                 mx = fmaxf(mx, sT[kb][r]);
;             }
;         mx = fmaxf(mx, __shfl_xor(mx, 32));
;         const float cand = fmaxf(mrun, mx * sl2);
;         const bool grew = __any(cand - mrun > 8.f);
;         const float mn = grew ? cand : mrun;
;         const float alpha = __builtin_amdgcn_exp2f(mrun - mn);
;         mrun = mn;
;         float ls = 0.f;
; #pragma unroll
;         for (int kb = 0; kb < 2; ++kb)
.LBB0_1167:
	s_and_b32 s16, 1, s12
	s_cselect_b32 s0, 0, 0xa800
	v_add_u32_e32 v189, s0, v187
	ds_read_b128 v[66:69], v189
	ds_read_b128 v[166:169], v189 offset:32
	ds_read_b128 v[70:73], v189 offset:12800
	ds_read_b128 v[170:173], v189 offset:12832
	ds_read_b128 v[174:177], v189 offset:64
	ds_read_b128 v[178:181], v189 offset:96
	ds_read_b128 v[216:219], v189 offset:12864
	ds_read_b128 v[220:223], v189 offset:12896
	v_mov_b32_e32 v248, v214
	ds_read_b128 v[224:227], v189 offset:128
	ds_read_b128 v[228:231], v189 offset:160
	ds_read_b128 v[232:235], v189 offset:12928
	ds_read_b128 v[236:239], v189 offset:12960
	s_waitcnt lgkmcnt(11)
	v_mfma_f32_32x32x16_bf16 v[82:97], v[66:69], v[142:145], 0
	s_waitcnt lgkmcnt(9)
	v_mfma_f32_32x32x16_bf16 v[66:81], v[70:73], v[142:145], 0
	v_mfma_f32_32x32x16_bf16 v[82:97], v[166:169], v[138:141], v[82:97]
	s_waitcnt lgkmcnt(8)
	v_mfma_f32_32x32x16_bf16 v[66:81], v[170:173], v[138:141], v[66:81]
	ds_read_b128 v[166:169], v189 offset:192
	ds_read_b128 v[170:173], v189 offset:224
	ds_read_b128 v[240:243], v189 offset:12992
	ds_read_b128 v[244:247], v189 offset:13024
	s_waitcnt lgkmcnt(11)
	v_mfma_f32_32x32x16_bf16 v[82:97], v[174:177], v[134:137], v[82:97]
	s_waitcnt lgkmcnt(9)
	v_mfma_f32_32x32x16_bf16 v[66:81], v[216:219], v[134:137], v[66:81]
	v_mfma_f32_32x32x16_bf16 v[82:97], v[178:181], v[130:133], v[82:97]
	s_waitcnt lgkmcnt(8)
	v_mfma_f32_32x32x16_bf16 v[66:81], v[220:223], v[130:133], v[66:81]
	ds_read_b128 v[174:177], v189 offset:256
	ds_read_b128 v[178:181], v189 offset:288
	ds_read_b128 v[216:219], v189 offset:13056
	ds_read_b128 v[220:223], v189 offset:13088
	s_waitcnt lgkmcnt(11)
	v_mfma_f32_32x32x16_bf16 v[82:97], v[224:227], v[126:129], v[82:97]
	s_waitcnt lgkmcnt(9)
	v_mfma_f32_32x32x16_bf16 v[66:81], v[232:235], v[126:129], v[66:81]
	v_mfma_f32_32x32x16_bf16 v[82:97], v[228:231], v[122:125], v[82:97]
	s_waitcnt lgkmcnt(8)
	v_mfma_f32_32x32x16_bf16 v[66:81], v[236:239], v[122:125], v[66:81]
	ds_read_b128 v[224:227], v189 offset:320
	ds_read_b128 v[228:231], v189 offset:352
	ds_read_b128 v[232:235], v189 offset:13120
	ds_read_b128 v[236:239], v189 offset:13152
	s_waitcnt lgkmcnt(11)
	v_mfma_f32_32x32x16_bf16 v[82:97], v[166:169], v[118:121], v[82:97]
	s_waitcnt lgkmcnt(9)
	v_mfma_f32_32x32x16_bf16 v[66:81], v[240:243], v[118:121], v[66:81]
	v_mfma_f32_32x32x16_bf16 v[82:97], v[170:173], v[114:117], v[82:97]
	s_waitcnt lgkmcnt(8)
	v_mfma_f32_32x32x16_bf16 v[66:81], v[244:247], v[114:117], v[66:81]
	s_waitcnt lgkmcnt(7)
	v_mfma_f32_32x32x16_bf16 v[82:97], v[174:177], v[110:113], v[82:97]
	s_waitcnt lgkmcnt(5)
	v_mfma_f32_32x32x16_bf16 v[66:81], v[216:219], v[110:113], v[66:81]
	v_mfma_f32_32x32x16_bf16 v[82:97], v[178:181], v[106:109], v[82:97]
	s_waitcnt lgkmcnt(4)
	v_mfma_f32_32x32x16_bf16 v[66:81], v[220:223], v[106:109], v[66:81]
	s_waitcnt lgkmcnt(3)
	v_mfma_f32_32x32x16_bf16 v[82:97], v[224:227], v[102:105], v[82:97]
	s_waitcnt lgkmcnt(1)
	v_mfma_f32_32x32x16_bf16 v[66:81], v[232:235], v[102:105], v[66:81]
	v_mfma_f32_32x32x16_bf16 v[82:97], v[228:231], v[98:101], v[82:97]
	s_waitcnt lgkmcnt(0)
	v_mfma_f32_32x32x16_bf16 v[66:81], v[236:239], v[98:101], v[66:81]
	v_add_u32_e32 v178, s0, v213
	v_add_u32_e32 v219, 0x6000, v178
	v_add_u32_e32 v218, 0x7000, v178
	v_add_u32_e32 v217, 0x8000, v178
	v_add_u32_e32 v216, 0x9000, v178
	ds_read2_b64 v[166:169], v219 offset0:128 offset1:130
	ds_read2_b64 v[170:173], v218 offset0:160 offset1:162
	ds_read2_b64 v[174:177], v217 offset0:192 offset1:194
	ds_read2_b64 v[178:181], v216 offset0:224 offset1:226
	v_max3_f32 v189, v82, s61, v83
	v_max3_f32 v189, v189, v84, v85
	v_max3_f32 v189, v189, v86, v87
	v_max3_f32 v189, v189, v88, v89
	v_max3_f32 v189, v189, v90, v91
	v_max3_f32 v189, v189, v92, v93
	v_max3_f32 v189, v189, v94, v95
	v_max3_f32 v189, v189, v96, v97
	v_max3_f32 v189, v189, v66, v67
	v_max3_f32 v189, v189, v68, v69
	v_max3_f32 v189, v189, v70, v71
	v_max3_f32 v189, v189, v72, v73
	v_max3_f32 v189, v189, v74, v75
	v_max3_f32 v189, v189, v76, v77
	v_max3_f32 v189, v189, v78, v79
	v_max3_f32 v189, v189, v80, v81
	ds_bpermute_b32 v214, v185, v189
	v_max_f32_e32 v220, v248, v248
	s_waitcnt lgkmcnt(0)
	v_max_f32_e32 v214, v214, v214
	v_max_f32_e32 v189, v189, v214
	v_mul_f32_e32 v189, 0x3dd53b94, v189
	v_max_f32_e32 v189, v220, v189
	v_sub_f32_e32 v214, v189, v248
	v_cmp_lt_f32_e32 vcc, s63, v214
	s_cmp_eq_u64 vcc, 0
	s_cselect_b64 s[0:1], -1, 0
	v_cndmask_b32_e64 v214, v189, v248, s[0:1]
	v_fma_f32 v82, v82, s80, -v214
	v_fma_f32 v83, v83, s80, -v214
	v_exp_f32_e32 v82, v82
	v_exp_f32_e32 v83, v83
	v_fma_f32 v84, v84, s80, -v214
	v_exp_f32_e32 v84, v84
	v_fma_f32 v85, v85, s80, -v214
	v_exp_f32_e32 v85, v85
	v_fma_f32 v86, v86, s80, -v214
	v_add_f32_e32 v189, 0, v82
	v_exp_f32_e32 v86, v86
	v_fma_f32 v87, v87, s80, -v214
	v_add_f32_e32 v189, v83, v189
	v_exp_f32_e32 v87, v87
	v_fma_f32 v88, v88, s80, -v214
	v_add_f32_e32 v189, v84, v189
	v_exp_f32_e32 v88, v88
	v_fma_f32 v89, v89, s80, -v214
	v_add_f32_e32 v189, v85, v189
	v_exp_f32_e32 v89, v89
	v_fma_f32 v90, v90, s80, -v214
	v_add_f32_e32 v189, v86, v189
	v_exp_f32_e32 v90, v90
	v_fma_f32 v91, v91, s80, -v214
	v_add_f32_e32 v189, v87, v189
	v_exp_f32_e32 v91, v91
	v_fma_f32 v92, v92, s80, -v214
	v_add_f32_e32 v189, v88, v189
	v_exp_f32_e32 v92, v92
	v_fma_f32 v93, v93, s80, -v214
	v_add_f32_e32 v189, v89, v189
	v_exp_f32_e32 v93, v93
	v_fma_f32 v94, v94, s80, -v214
	v_add_f32_e32 v189, v90, v189
	v_exp_f32_e32 v94, v94
	v_fma_f32 v95, v95, s80, -v214
	v_add_f32_e32 v189, v91, v189
	v_exp_f32_e32 v95, v95
	v_fma_f32 v96, v96, s80, -v214
	v_add_f32_e32 v189, v92, v189
	v_exp_f32_e32 v96, v96
; template <int DQK, bool SWA>
; DI void attn_item(const P& p, char* shm, int b, int head, int qtile) {
;     ...
;         float ls = 0.f;
; #pragma unroll
;         for (int kb = 0; kb < 2; ++kb)
; #pragma unroll
;             for (int r = 0; r < 16; ++r) { const float pv = __builtin_amdgcn_exp2f(fmaf(sT[kb][r], sl2, -mn)); sT[kb][r] = pv; ls += pv; }
;         ls += __shfl_xor(ls, 32);
;         lrun = lrun * alpha + ls;
;         if (grew) {
; #pragma unroll
;             for (int v = 0; v < 4; ++v) oT[v] *= alpha;
;         }
	v_fma_f32 v97, v97, s80, -v214
	v_add_f32_e32 v189, v93, v189
	v_exp_f32_e32 v97, v97
	v_fma_f32 v66, v66, s80, -v214
	v_add_f32_e32 v189, v94, v189
	v_exp_f32_e32 v220, v66
	v_fma_f32 v66, v67, s80, -v214
	v_add_f32_e32 v189, v95, v189
	v_exp_f32_e32 v67, v66
	v_fma_f32 v66, v68, s80, -v214
	v_add_f32_e32 v189, v96, v189
	v_exp_f32_e32 v68, v66
	v_fma_f32 v66, v69, s80, -v214
	v_add_f32_e32 v189, v97, v189
	v_exp_f32_e32 v69, v66
	v_fma_f32 v70, v70, s80, -v214
	v_add_f32_e32 v66, v220, v189
	v_exp_f32_e32 v70, v70
	v_fma_f32 v71, v71, s80, -v214
	v_add_f32_e32 v66, v67, v66
	v_exp_f32_e32 v71, v71
	v_fma_f32 v72, v72, s80, -v214
	v_add_f32_e32 v66, v68, v66
	v_exp_f32_e32 v72, v72
	v_fma_f32 v73, v73, s80, -v214
	v_add_f32_e32 v66, v69, v66
	v_exp_f32_e32 v73, v73
	v_fma_f32 v74, v74, s80, -v214
	v_add_f32_e32 v66, v70, v66
	v_exp_f32_e32 v74, v74
	v_fma_f32 v75, v75, s80, -v214
	v_add_f32_e32 v66, v71, v66
	v_exp_f32_e32 v75, v75
	v_fma_f32 v76, v76, s80, -v214
	v_add_f32_e32 v66, v72, v66
	v_exp_f32_e32 v76, v76
	v_fma_f32 v77, v77, s80, -v214
	v_add_f32_e32 v66, v73, v66
	v_exp_f32_e32 v77, v77
	v_fma_f32 v78, v78, s80, -v214
	v_add_f32_e32 v66, v74, v66
	v_exp_f32_e32 v78, v78
	v_fma_f32 v79, v79, s80, -v214
	v_add_f32_e32 v66, v75, v66
	v_exp_f32_e32 v79, v79
	v_fma_f32 v80, v80, s80, -v214
	v_add_f32_e32 v66, v76, v66
	v_exp_f32_e32 v80, v80
	v_fma_f32 v81, v81, s80, -v214
	v_add_f32_e32 v66, v77, v66
	v_exp_f32_e32 v81, v81
	v_add_f32_e32 v66, v78, v66
	v_add_f32_e32 v66, v79, v66
	v_add_f32_e32 v66, v80, v66
	v_add_f32_e32 v189, v81, v66
	v_sub_f32_e32 v222, v248, v214
	ds_bpermute_b32 v221, v185, v189
	v_exp_f32_e32 v66, v222
	s_cbranch_vccz .LBB0_1169
	v_pk_mul_f32 v[64:65], v[64:65], v[66:67] op_sel_hi:[1,0]
	v_pk_mul_f32 v[62:63], v[62:63], v[66:67] op_sel_hi:[1,0]
	v_pk_mul_f32 v[60:61], v[60:61], v[66:67] op_sel_hi:[1,0]
	v_pk_mul_f32 v[58:59], v[58:59], v[66:67] op_sel_hi:[1,0]
	v_pk_mul_f32 v[56:57], v[56:57], v[66:67] op_sel_hi:[1,0]
	v_pk_mul_f32 v[54:55], v[54:55], v[66:67] op_sel_hi:[1,0]
	v_pk_mul_f32 v[52:53], v[52:53], v[66:67] op_sel_hi:[1,0]
	v_pk_mul_f32 v[50:51], v[50:51], v[66:67] op_sel_hi:[1,0]
	v_pk_mul_f32 v[48:49], v[48:49], v[66:67] op_sel_hi:[1,0]
	v_pk_mul_f32 v[46:47], v[46:47], v[66:67] op_sel_hi:[1,0]
	v_pk_mul_f32 v[44:45], v[44:45], v[66:67] op_sel_hi:[1,0]
	v_pk_mul_f32 v[42:43], v[42:43], v[66:67] op_sel_hi:[1,0]
	v_pk_mul_f32 v[40:41], v[40:41], v[66:67] op_sel_hi:[1,0]
	v_pk_mul_f32 v[38:39], v[38:39], v[66:67] op_sel_hi:[1,0]
	v_pk_mul_f32 v[36:37], v[36:37], v[66:67] op_sel_hi:[1,0]
	v_pk_mul_f32 v[34:35], v[34:35], v[66:67] op_sel_hi:[1,0]
	v_pk_mul_f32 v[32:33], v[32:33], v[66:67] op_sel_hi:[1,0]
	v_pk_mul_f32 v[30:31], v[30:31], v[66:67] op_sel_hi:[1,0]
	v_pk_mul_f32 v[28:29], v[28:29], v[66:67] op_sel_hi:[1,0]
	v_pk_mul_f32 v[26:27], v[26:27], v[66:67] op_sel_hi:[1,0]
	v_pk_mul_f32 v[24:25], v[24:25], v[66:67] op_sel_hi:[1,0]
	v_pk_mul_f32 v[22:23], v[22:23], v[66:67] op_sel_hi:[1,0]
	v_pk_mul_f32 v[20:21], v[20:21], v[66:67] op_sel_hi:[1,0]
	v_pk_mul_f32 v[18:19], v[18:19], v[66:67] op_sel_hi:[1,0]
	v_pk_mul_f32 v[16:17], v[16:17], v[66:67] op_sel_hi:[1,0]
	v_pk_mul_f32 v[14:15], v[14:15], v[66:67] op_sel_hi:[1,0]
	v_pk_mul_f32 v[12:13], v[12:13], v[66:67] op_sel_hi:[1,0]
	v_pk_mul_f32 v[10:11], v[10:11], v[66:67] op_sel_hi:[1,0]
	v_pk_mul_f32 v[8:9], v[8:9], v[66:67] op_sel_hi:[1,0]
	v_pk_mul_f32 v[6:7], v[6:7], v[66:67] op_sel_hi:[1,0]
	v_pk_mul_f32 v[4:5], v[4:5], v[66:67] op_sel_hi:[1,0]
	v_pk_mul_f32 v[2:3], v[2:3], v[66:67] op_sel_hi:[1,0]
; #define MFMA32(a, b, c) __builtin_amdgcn_mfma_f32_32x32x16_bf16((a), (b), (c), 0, 0, 0)
; template <int DQK, bool SWA>
; DI void attn_item(const P& p, char* shm, int b, int head, int qtile) {
;     ...
;         ls += __shfl_xor(ls, 32);
;         lrun = lrun * alpha + ls;
;         if (grew) {
; #pragma unroll
;             for (int v = 0; v < 4; ++v) oT[v] *= alpha;
;         }
;         bf16x8 pf[2][2];
; #pragma unroll
;         for (int kb = 0; kb < 2; ++kb)
; #pragma unroll
;             for (int s2 = 0; s2 < 2; ++s2)
;                 pf[kb][s2] = pack8(sT[kb][8 * s2], sT[kb][8 * s2 + 1], sT[kb][8 * s2 + 2], sT[kb][8 * s2 + 3], sT[kb][8 * s2 + 4], sT[kb][8 * s2 + 5], sT[kb][8 * s2 + 6], sT[kb][8 * s2 + 7]);
;         if (t + 1 < ntiles) store_tile(t + 1);
;         if (t + 2 < ntiles) load_tile(t + 2);
;         {
;             __builtin_amdgcn_s_setprio(1);
; #pragma unroll
;             for (int g = 0; g < 4; ++g) {
;                 if (g + 1 < 4) {
; #pragma unroll
;                     for (int v = 0; v < 4; ++v) va[(g + 1) & 1][v] = vfrag(g + 1, v);
;                 }
;                 __builtin_amdgcn_sched_barrier(0);
; #pragma unroll
;                 for (int v = 0; v < 4; ++v) oT[v] = MFMA32(va[g & 1][v], pf[g >> 1][g & 1], oT[v]);
;                 __builtin_amdgcn_sched_barrier(0);
;             }
;             __builtin_amdgcn_s_setprio(0);
;         }
;         __syncthreads();
.LBB0_1169:
	s_cmp_eq_u32 s16, 1
	s_cselect_b32 s0, 0xa800, 0
	s_add_i32 s0, s0, 16
	v_add_u32_e32 v222, s0, v190
	s_waitcnt vmcnt(4)
	ds_write_b128 v222, v[146:149]
	v_add_u32_e32 v146, s0, v192
	s_waitcnt vmcnt(3)
	ds_write_b128 v146, v[150:153]
	v_add_u32_e32 v146, s0, v188
	s_waitcnt vmcnt(2)
	ds_write_b128 v146, v[154:157] offset:256
	v_add_u32_e32 v146, s0, v184
	v_add_u32_e32 v146, 0x6400, v146
	s_waitcnt vmcnt(1)
	ds_write2_b64 v146, v[162:163], v[164:165] offset1:1
	v_add_u32_e32 v146, s0, v186
	v_add_u32_e32 v146, 0x6400, v146
	s_waitcnt vmcnt(0)
	ds_write2_b64 v146, v[158:159], v[160:161] offset1:1
	v_lshl_add_u64 v[146:147], s[26:27], 0, v[200:201]
	v_lshl_add_u64 v[150:151], s[26:27], 0, v[202:203]
	v_lshl_add_u64 v[154:155], s[26:27], 0, v[198:199]
	v_lshl_add_u64 v[158:159], s[26:27], 0, v[194:195]
	global_load_dwordx4 v[146:149], v[146:147], off
	s_nop 0
	global_load_dwordx4 v[150:153], v[150:151], off
	s_nop 0
	global_load_dwordx4 v[154:157], v[154:155], off
	s_nop 0
	global_load_dwordx4 v[162:165], v[158:159], off
	v_lshl_add_u64 v[158:159], s[26:27], 0, v[196:197]
	global_load_dwordx4 v[158:161], v[158:159], off
	s_waitcnt lgkmcnt(5)
	v_add_f32_e32 v189, v189, v221
	v_fmac_f32_e32 v189, v215, v66
	v_cvt_pk_bf16_f32 v82, v82, v83
	v_cvt_pk_bf16_f32 v83, v84, v85
	v_cvt_pk_bf16_f32 v84, v86, v87
	v_cvt_pk_bf16_f32 v85, v88, v89
	v_cvt_pk_bf16_f32 v86, v90, v91
	v_cvt_pk_bf16_f32 v87, v92, v93
	v_cvt_pk_bf16_f32 v88, v94, v95
	v_cvt_pk_bf16_f32 v89, v96, v97
	v_cvt_pk_bf16_f32 v66, v220, v67
	v_cvt_pk_bf16_f32 v67, v68, v69
	v_cvt_pk_bf16_f32 v68, v70, v71
	v_cvt_pk_bf16_f32 v69, v72, v73
	v_cvt_pk_bf16_f32 v70, v74, v75
	v_cvt_pk_bf16_f32 v71, v76, v77
	v_cvt_pk_bf16_f32 v72, v78, v79
	v_cvt_pk_bf16_f32 v73, v80, v81
	ds_read2_b64 v[74:77], v219 offset0:132 offset1:134
	ds_read2_b64 v[78:81], v218 offset0:164 offset1:166
	ds_read2_b64 v[90:93], v217 offset0:196 offset1:198
	ds_read2_b64 v[94:97], v216 offset0:228 offset1:230
	v_mfma_f32_32x32x16_bf16 v[50:65], v[166:169], v[82:85], v[50:65]
	v_mfma_f32_32x32x16_bf16 v[34:49], v[170:173], v[82:85], v[34:49]
	v_mfma_f32_32x32x16_bf16 v[18:33], v[174:177], v[82:85], v[18:33]
	v_mfma_f32_32x32x16_bf16 v[2:17], v[178:181], v[82:85], v[2:17]
	ds_read2_b64 v[82:85], v219 offset0:136 offset1:138
	ds_read2_b64 v[166:169], v218 offset0:168 offset1:170
	ds_read2_b64 v[170:173], v217 offset0:200 offset1:202
	ds_read2_b64 v[174:177], v216 offset0:232 offset1:234
	s_waitcnt lgkmcnt(7)
	v_mfma_f32_32x32x16_bf16 v[50:65], v[74:77], v[86:89], v[50:65]
	s_waitcnt lgkmcnt(6)
	v_mfma_f32_32x32x16_bf16 v[34:49], v[78:81], v[86:89], v[34:49]
	s_waitcnt lgkmcnt(5)
	v_mfma_f32_32x32x16_bf16 v[18:33], v[90:93], v[86:89], v[18:33]
	s_waitcnt lgkmcnt(4)
	v_mfma_f32_32x32x16_bf16 v[2:17], v[94:97], v[86:89], v[2:17]
	ds_read2_b64 v[74:77], v219 offset0:140 offset1:142
	ds_read2_b64 v[78:81], v218 offset0:172 offset1:174
	ds_read2_b64 v[86:89], v217 offset0:204 offset1:206
	ds_read2_b64 v[90:93], v216 offset0:236 offset1:238
	s_waitcnt lgkmcnt(7)
	v_mfma_f32_32x32x16_bf16 v[50:65], v[82:85], v[66:69], v[50:65]
	s_waitcnt lgkmcnt(6)
	v_mfma_f32_32x32x16_bf16 v[34:49], v[166:169], v[66:69], v[34:49]
	s_waitcnt lgkmcnt(5)
	v_mfma_f32_32x32x16_bf16 v[18:33], v[170:173], v[66:69], v[18:33]
	s_waitcnt lgkmcnt(4)
	v_mfma_f32_32x32x16_bf16 v[2:17], v[174:177], v[66:69], v[2:17]
	s_waitcnt lgkmcnt(3)
	v_mfma_f32_32x32x16_bf16 v[50:65], v[74:77], v[70:73], v[50:65]
	s_waitcnt lgkmcnt(2)
	v_mfma_f32_32x32x16_bf16 v[34:49], v[78:81], v[70:73], v[34:49]
	s_waitcnt lgkmcnt(1)
	v_mfma_f32_32x32x16_bf16 v[18:33], v[86:89], v[70:73], v[18:33]
	s_waitcnt lgkmcnt(0)
	v_mfma_f32_32x32x16_bf16 v[2:17], v[90:93], v[70:73], v[2:17]
	s_add_i32 s12, s12, 1
	s_mov_b64 s[0:1], 0x2000
	v_lshl_add_u64 v[194:195], v[194:195], 0, s[14:15]
	v_lshl_add_u64 v[196:197], v[196:197], 0, s[14:15]
	v_lshl_add_u64 v[198:199], v[198:199], 0, s[0:1]
	v_lshl_add_u64 v[200:201], v[200:201], 0, s[14:15]
	s_cmpk_eq_i32 s12, 0x43
	v_lshl_add_u64 v[202:203], v[202:203], 0, s[14:15]
	s_barrier
	s_cbranch_scc1 .LBB0_1171
	v_mov_b32_e32 v215, v189
	s_branch .LBB0_1167
